# diff-attention unit start: g_mlp row loaded at the P1 exit (before the team barrier) instead of load-wait-write at the unit start
# baseline (speedup 1.0000x reference)
; template <int THRL> ...
;     ...
;   if (SJ.n > 0) { *(pg8::f32x4*)(shm + att::LDS_SJ_G + tid * 16) = *(const pg8::f32x4*)(SJ.g_mlp + tid * 4); }
; __global__ void __launch_bounds__(NWAVES * 64, 2) mega_fwd(Args args) {
;     ...
;         const float d1 = wave_sum(lq1[lane] * lk1[lane]), d2 = wave_sum(lq2[lane] * lk2[lane]);
.LBB0_296:
	s_waitcnt vmcnt(0)
	s_barrier
	v_lshlrev_b32_e32 v240, 2, v0
	v_ashrrev_i32_e32 v241, 31, v240
	v_lshl_add_u64 v[240:241], v[240:241], 2, s[60:61]
	global_load_dwordx4 v[236:239], v[240:241], off
	v_lshlrev_b32_e32 v253, 2, v194
	global_load_dword v249, v253, s[14:15]
	global_load_dword v250, v253, s[16:17]
	global_load_dword v251, v253, s[18:19]
	global_load_dword v252, v253, s[20:21]

; template <int THRL> ...
;     ...
;   if (SJ.n > 0) { *(pg8::f32x4*)(shm + att::LDS_SJ_G + tid * 16) = *(const pg8::f32x4*)(SJ.g_mlp + tid * 4); }
.LBB0_399:
	v_mov_b32_e32 v2, v0
	s_and_b64 vcc, exec, s[4:5]
	v_readfirstlane_b32 s0, v2
	v_lshlrev_b32_e32 v3, 4, v2
	s_cbranch_vccnz .LBB0_401
	v_lshlrev_b32_e32 v4, 2, v2
	v_ashrrev_i32_e32 v5, 31, v4
	v_lshl_add_u64 v[4:5], v[4:5], 2, s[60:61]
	v_add_u32_e32 v8, 0, v3
	v_add_u32_e32 v8, 0x24800, v8
	s_waitcnt vmcnt(0)
	ds_write_b128 v8, v[236:239]
